# v1: phase-0 share of cache shift copy moved into idle CUs of the four FFN-out second rounds
# speedup vs baseline: 1.0232x; 1.0232x over previous
_Z8yoco_fwd6Params:
	s_load_dwordx16 s[12:27], s[0:1], 0x0
	s_load_dwordx16 s[36:51], s[0:1], 0x40
	s_load_dwordx16 s[52:67], s[0:1], 0x80
	s_load_dwordx8 s[68:75], s[0:1], 0xc0
	s_load_dword s78, s[0:1], 0xe0
	v_and_b32_e32 v174, 0x3ff, v0
	s_add_u32 s8, s0, 0xe0
	v_mov_b32_e32 v70, v174
	s_addc_u32 s9, s1, 0
	s_lshl_b32 s33, s2, 3
	v_ashrrev_i32_e32 v67, 6, v70
	s_movk_i32 s0, 0x2100
	v_and_b32_e32 v66, 63, v70
	v_add_u32_e32 v68, s33, v67
	v_mul_lo_u32 v1, v67, s0
	s_movk_i32 s0, 0x5000
	s_mov_b32 s79, 0
	s_waitcnt lgkmcnt(0)
	v_mov_b32_e32 v235, s18
	v_mov_b32_e32 v236, s19
	v_mov_b32_e32 v237, s20
	v_mov_b32_e32 v238, s21
	v_mov_b32_e32 v239, s72
	v_mov_b32_e32 v240, s73
	s_lshl_b32 s76, s78, 3
	v_ashrrev_i32_e32 v71, 31, v70
	v_add_u32_e32 v124, 0, v1
	v_cmp_gt_i32_e32 vcc, s0, v68
	v_lshrrev_b32_e32 v1, 3, v66
	v_lshlrev_b32_e32 v72, 3, v66
	v_mov_b32_e32 v110, v68
	s_and_saveexec_b64 s[10:11], vcc
	s_cbranch_execz .LBB0_96
	v_and_b32_e32 v80, 56, v72
	v_lshrrev_b32_e32 v76, 5, v66
	v_mul_u32_u24_e32 v3, 0x84, v80
	v_lshlrev_b32_e32 v6, 2, v1
	s_movk_i32 s3, 0x84
	v_add3_u32 v79, v124, v3, v6
	v_or_b32_e32 v127, 2, v76
	v_mov_b32_e32 v3, 0x108
	v_mad_u32_u24 v130, v127, s3, v3
	v_mov_b32_e32 v3, 0x318
	v_mad_u32_u24 v132, v127, s3, v3
	v_mov_b32_e32 v3, 0x528
	v_mad_u32_u24 v133, v127, s3, v3
	v_mov_b32_e32 v3, 0x630
	v_mad_u32_u24 v6, v127, s3, v3
	v_mov_b32_e32 v3, 0x738
	v_mad_u32_u24 v134, v127, s3, v3
	v_mov_b32_e32 v3, 0x948
	v_mad_u32_u24 v135, v127, s3, v3
	v_mov_b32_e32 v3, 0xb58
	v_mad_u32_u24 v136, v127, s3, v3
	v_mov_b32_e32 v3, 0xc60
	v_mad_u32_u24 v7, v127, s3, v3
	v_mov_b32_e32 v3, 0xd68
	v_mad_u32_u24 v137, v127, s3, v3
	v_mov_b32_e32 v3, 0xf78
	v_mad_u32_u24 v138, v127, s3, v3
	v_mov_b32_e32 v3, 0x1188
	v_mad_u32_u24 v139, v127, s3, v3
	v_mov_b32_e32 v3, 0x1290
	v_mov_b32_e32 v75, 0
	v_and_b32_e32 v78, 31, v70
	v_mad_u32_u24 v8, v127, s3, v3
	v_mov_b32_e32 v3, 0x1398
	v_lshlrev_b32_e32 v2, 2, v78
	v_lshlrev_b32_e32 v74, 1, v80
	v_mad_u32_u24 v140, v127, s3, v3
	v_mov_b32_e32 v3, v75
	v_add_u32_e32 v69, v124, v2
	v_lshl_add_u64 v[4:5], s[74:75], 0, v[74:75]
	s_mov_b64 s[0:1], 0x4f00000
	v_lshl_add_u64 v[90:91], s[68:69], 0, v[2:3]
	v_lshl_add_u64 v[92:93], s[66:67], 0, v[2:3]
	v_lshl_add_u64 v[94:95], s[64:65], 0, v[2:3]
	v_lshl_add_u64 v[96:97], s[60:61], 0, v[2:3]
	v_lshlrev_b32_e32 v2, 1, v67
	v_lshl_add_u64 v[82:83], v[4:5], 0, s[0:1]
	s_mov_b64 s[0:1], 0x4c00000
	s_add_u32 s28, s42, 0x1000
	v_lshl_add_u32 v141, s2, 4, v2
	v_lshlrev_b32_e32 v2, 5, v67
	v_lshl_add_u64 v[84:85], v[4:5], 0, s[0:1]
	s_mov_b64 s[0:1], 0x4600000
	s_addc_u32 s29, s43, 0
	v_lshl_add_u32 v142, s2, 8, v2
	v_lshlrev_b32_e32 v2, 8, v67
	v_lshl_add_u64 v[86:87], v[4:5], 0, s[0:1]
	s_mov_b64 s[0:1], 0x4200000
	s_cmp_lg_u64 s[62:63], 0
	v_lshl_add_u32 v143, s2, 11, v2
	v_lshlrev_b32_e32 v2, 4, v67
	v_mad_u32_u24 v73, v76, s3, v69
	v_or_b32_e32 v81, 8, v1
	v_or_b32_e32 v125, 16, v1
	v_or_b32_e32 v126, 24, v1
	v_mul_u32_u24_e32 v128, 0x84, v127
	v_or_b32_e32 v129, 4, v76
	v_or_b32_e32 v131, 6, v76
	v_lshl_add_u64 v[88:89], v[4:5], 0, s[0:1]
	s_cselect_b64 s[30:31], -1, 0
	v_mov_b32_e32 v77, v75
	s_lshl_b32 s3, s78, 4
	s_lshl_b32 s77, s78, 8
	s_lshl_b32 s84, s78, 11
	v_lshl_add_u32 v144, s2, 7, v2
	s_lshl_b32 s85, s78, 7
	s_mov_b32 s86, 0
	s_mov_b32 s87, 0x2ad5802b
	s_movk_i32 s88, 0x5fa
	s_mov_b32 s93, 0x18000
	s_mov_b32 s95, 0x24000
	v_or_b32_e32 v145, 8, v76
	v_or_b32_e32 v146, 10, v76
	v_or_b32_e32 v147, 12, v76
	s_mov_b32 s97, 0x30000
	v_or_b32_e32 v148, 14, v76
	v_or_b32_e32 v149, 16, v76
	v_or_b32_e32 v150, 18, v76
	v_or_b32_e32 v151, 20, v76
	s_mov_b32 s91, 0x3c000
	v_or_b32_e32 v152, 22, v76
	v_or_b32_e32 v153, 24, v76
	v_or_b32_e32 v154, 26, v76
	v_or_b32_e32 v155, 28, v76
	s_mov_b32 s94, 0x48000
	v_or_b32_e32 v156, 30, v76
	v_or_b32_e32 v157, 32, v76
	v_or_b32_e32 v158, 34, v76
	v_or_b32_e32 v159, 36, v76
	v_or_b32_e32 v160, 38, v76
	v_or_b32_e32 v161, 40, v76
	v_or_b32_e32 v162, 42, v76
	v_add_u32_e32 v163, v69, v6
	v_add_u32_e32 v164, v69, v7
	v_add_u32_e32 v165, v69, v8
	v_or_b32_e32 v166, 44, v76
	v_or_b32_e32 v167, 46, v76
	v_or_b32_e32 v168, 48, v76
	v_or_b32_e32 v169, 50, v76
	v_or_b32_e32 v170, 52, v76
	v_or_b32_e32 v171, 54, v76
	v_or_b32_e32 v172, 56, v76
	v_or_b32_e32 v173, 58, v76
	v_or_b32_e32 v175, 60, v76
	v_or_b32_e32 v176, 62, v76
	v_add_u32_e32 v177, s76, v67
	v_mov_b32_e32 v178, 0x3700000
	v_mov_b32_e32 v179, 0x2c00000
	v_mov_b32_e32 v180, 6
	v_mov_b32_e32 v181, 5
	v_mov_b32_e32 v182, 0x1600000
	v_mov_b32_e32 v183, 0x1f210000
	v_mov_b32_e32 v184, 0x7210000
	v_mov_b32_e32 v185, v67
	v_mov_b32_e32 v186, v67
	s_mov_b32 s90, 0x54000
	s_mov_b32 s92, 0xb00000
	s_mov_b32 s96, 0x2e8ba2e9
	s_movk_i32 s89, 0x5800
	s_mov_b64 s[34:35], 0
	s_mov_b64 s[60:61], 0xc000
	s_branch .LBB0_3

.LBB0_96:
	s_or_b64 exec, exec, s[10:11]
	s_add_u32 s38, s74, 0x5000000
	s_addc_u32 s39, s75, 0
	s_add_u32 s40, s74, 0x9100000
	s_addc_u32 s41, s75, 0
	s_add_u32 s6, s74, 0x12b60000
	s_movk_i32 s0, 0x4100
	s_addc_u32 s7, s75, 0
	v_cmp_gt_i32_e32 vcc, s0, v68
	v_mbcnt_lo_u32_b32 v175, -1, 0
	s_and_saveexec_b64 s[10:11], vcc
	s_cbranch_execz .LBB0_108
	s_waitcnt vmcnt(1)
	v_mov_b32_e32 v35, 0
	v_ashrrev_i32_e32 v69, 31, v68
	v_lshlrev_b32_e32 v34, 4, v66
	v_mov_b32_e32 v73, v35
	s_ashr_i32 s77, s76, 31
	v_lshlrev_b64 v[2:3], 12, v[68:69]
	v_cmp_eq_u32_e64 s[0:1], 0, v66
	v_lshl_add_u64 v[36:37], s[38:39], 0, v[34:35]
	v_lshl_add_u64 v[38:39], s[40:41], 0, v[72:73]
	v_lshlrev_b32_e32 v48, 9, v110
	s_lshl_b32 s3, s76, 9
	v_lshl_add_u64 v[40:41], s[12:13], 0, v[2:3]
	s_lshl_b64 s[22:23], s[76:77], 12
	s_mov_b64 s[12:13], 0
	s_mov_b32 s28, 0
	s_mov_b32 s29, 0x2ad5802b
	s_movk_i32 s30, 0x5fa
	s_mov_b64 s[24:25], 0xc000
	s_movk_i32 s31, 0x3fff
	v_mbcnt_hi_u32_b32 v49, -1, v175
	s_movk_i32 s34, 0x40ff
	v_lshlrev_b32_e32 v34, 4, v66
	v_mov_b32_e32 v50, 0x1f210000
	v_mov_b32_e32 v51, 0x7210000
	v_mov_b64_e32 v[42:43], v[68:69]
	s_branch .LBB0_99

.LBB0_148:
	s_or_b64 exec, exec, s[0:1]
	s_add_u32 s50, s74, 0x29265c00
	s_movk_i32 s0, 0x1a00
	s_addc_u32 s51, s75, 0
	v_cmp_gt_i32_e32 vcc, s0, v68
	s_and_saveexec_b64 s[10:11], vcc
	s_cbranch_execz .LBB0_168
	v_and_b32_e32 v2, 56, v3
	v_mov_b32_e32 v71, 0
	s_movk_i32 s0, 0x84
	v_lshl_add_u32 v3, v2, 1, v124
	v_mul_u32_u24_e32 v4, 0x84, v1
	v_lshlrev_b32_e32 v70, 2, v66
	v_lshlrev_b32_e32 v5, 6, v67
	v_mad_u32_u24 v69, v66, s0, v124
	v_lshl_add_u64 v[72:73], s[20:21], 0, v[70:71]
	v_lshl_add_u32 v67, s2, 9, v5
	s_lshl_b32 s24, s76, 6
	s_mov_b64 s[12:13], 0
	s_mov_b32 s25, 0x4ec4ec4f
	s_movk_i32 s26, 0xff30
	s_movk_i32 s27, 0x4f
	s_mov_b32 s28, 0
	s_mov_b32 s29, 0x2ad5802b
	s_movk_i32 s30, 0x5fa
	s_mov_b64 s[14:15], 0xc000
	s_movk_i32 s31, 0x800
	s_mov_b32 s34, 0x44000
	v_lshlrev_b32_e32 v74, 1, v2
	v_add_u32_e32 v111, v3, v4
	s_movk_i32 s35, 0x19ff
	v_mov_b32_e32 v112, 0x780
	v_mov_b32_e32 v113, 0x1f210000
	v_mov_b32_e32 v114, 0x7210000
	s_branch .LBB0_151

.LBB0_168:
	s_or_b64 exec, exec, s[10:11]
	s_mov_b32 s0, 0
	v_cmp_gt_i32_e32 vcc, s0, v110
	s_and_saveexec_b64 s[4:5], vcc
	s_cbranch_execz .LBB0_171
	v_mov_b32_e32 v3, 0
	v_lshlrev_b32_e32 v1, 9, v110
	s_lshl_b32 s14, s76, 9
	s_mov_b64 s[10:11], 0
	s_mov_b32 s15, 0x2ad5802b
	v_mov_b32_e32 v6, s21
	v_mov_b32_e32 v7, s19
	v_mov_b32_e32 v8, s20
	v_mov_b32_e32 v9, s18
	v_lshlrev_b32_e32 v4, 4, v66
	v_mov_b32_e32 v5, v3
	s_mov_b64 s[12:13], 0xc000
	s_mov_b32 s22, 0xd000
	s_waitcnt vmcnt(4)
	v_mov_b32_e32 v10, 0x1f210000
	v_mov_b32_e32 v11, 0x7210000
	s_mov_b32 s23, 0xf67f

.LBB0_263:
	s_cmp_lt_u32 s33, 32
	s_cbranch_scc1 .Lcpy1_end
	v_lshrrev_b32_e32 v21, 6, v174
	v_and_b32_e32 v22, 63, v174
	v_lshlrev_b32_e32 v22, 4, v22
	v_readfirstlane_b32 s80, v21
	v_add_u32_e32 v23, 0x1000, v22
	v_readfirstlane_b32 s92, v235
	v_readfirstlane_b32 s93, v236
	v_readfirstlane_b32 s94, v237
	v_readfirstlane_b32 s95, v238
	v_readfirstlane_b32 s98, v239
	v_readfirstlane_b32 s99, v240
	s_add_i32 s80, s80, s33
	s_add_i32 s80, s80, 0xffffffe0
	s_sub_i32 s100, s78, 4
	s_lshl_b32 s100, s100, 3
.Lcpy1_loop:
	s_add_i32 s101, s80, s100
	s_cmp_lt_u32 s101, 0x3da0
	s_cbranch_scc0 .Lcpy1_tail
	s_mul_hi_u32 s81, s80, 0x2ad5802b
	s_lshr_b32 s81, s81, 8
	s_mul_i32 s82, s81, 0x5fa
	s_sub_i32 s82, s80, s82
	s_lshl_b32 s82, s82, 13
	s_and_b32 s83, s81, 31
	s_mul_i32 s83, s83, 0xc00000
	s_add_i32 s82, s82, s83
	s_cmp_lt_u32 s81, 32
	s_cselect_b32 s84, s92, s94
	s_cselect_b32 s85, s93, s95
	s_mov_b32 s83, 0x1f210000
	s_cselect_b32 s83, 0x7210000, s83
	s_add_u32 s84, s84, s82
	s_addc_u32 s85, s85, 0
	s_add_u32 s84, s84, 0xc000
	s_addc_u32 s85, s85, 0
	s_add_u32 s83, s83, s82
	s_add_u32 s86, s98, s83
	s_addc_u32 s87, s99, 0
	s_mul_hi_u32 s81, s101, 0x2ad5802b
	s_lshr_b32 s81, s81, 8
	s_mul_i32 s82, s81, 0x5fa
	s_sub_i32 s82, s101, s82
	s_lshl_b32 s82, s82, 13
	s_and_b32 s83, s81, 31
	s_mul_i32 s83, s83, 0xc00000
	s_add_i32 s82, s82, s83
	s_cmp_lt_u32 s81, 32
	s_cselect_b32 s88, s92, s94
	s_cselect_b32 s89, s93, s95
	s_mov_b32 s83, 0x1f210000
	s_cselect_b32 s83, 0x7210000, s83
	s_add_u32 s88, s88, s82
	s_addc_u32 s89, s89, 0
	s_add_u32 s88, s88, 0xc000
	s_addc_u32 s89, s89, 0
	s_add_u32 s83, s83, s82
	s_add_u32 s90, s98, s83
	s_addc_u32 s91, s99, 0
	global_load_dwordx4 v[64:67], v22, s[84:85] nt
	global_load_dwordx4 v[68:71], v22, s[84:85] offset:1024 nt
	global_load_dwordx4 v[72:75], v22, s[84:85] offset:2048 nt
	global_load_dwordx4 v[76:79], v22, s[84:85] offset:3072 nt
	global_load_dwordx4 v[80:83], v23, s[84:85] nt
	global_load_dwordx4 v[84:87], v23, s[84:85] offset:1024 nt
	global_load_dwordx4 v[88:91], v23, s[84:85] offset:2048 nt
	global_load_dwordx4 v[92:95], v23, s[84:85] offset:3072 nt
	global_load_dwordx4 v[96:99], v22, s[88:89] nt
	global_load_dwordx4 v[100:103], v22, s[88:89] offset:1024 nt
	global_load_dwordx4 v[104:107], v22, s[88:89] offset:2048 nt
	global_load_dwordx4 v[108:111], v22, s[88:89] offset:3072 nt
	global_load_dwordx4 v[112:115], v23, s[88:89] nt
	global_load_dwordx4 v[116:119], v23, s[88:89] offset:1024 nt
	global_load_dwordx4 v[120:123], v23, s[88:89] offset:2048 nt
	global_load_dwordx4 v[124:127], v23, s[88:89] offset:3072 nt
	s_waitcnt vmcnt(15)
	global_store_dwordx4 v22, v[64:67], s[86:87] nt
	s_waitcnt vmcnt(15)
	global_store_dwordx4 v22, v[68:71], s[86:87] offset:1024 nt
	s_waitcnt vmcnt(15)
	global_store_dwordx4 v22, v[72:75], s[86:87] offset:2048 nt
	s_waitcnt vmcnt(15)
	global_store_dwordx4 v22, v[76:79], s[86:87] offset:3072 nt
	s_waitcnt vmcnt(15)
	global_store_dwordx4 v23, v[80:83], s[86:87] nt
	s_waitcnt vmcnt(15)
	global_store_dwordx4 v23, v[84:87], s[86:87] offset:1024 nt
	s_waitcnt vmcnt(15)
	global_store_dwordx4 v23, v[88:91], s[86:87] offset:2048 nt
	s_waitcnt vmcnt(15)
	global_store_dwordx4 v23, v[92:95], s[86:87] offset:3072 nt
	s_waitcnt vmcnt(15)
	global_store_dwordx4 v22, v[96:99], s[90:91] nt
	s_waitcnt vmcnt(15)
	global_store_dwordx4 v22, v[100:103], s[90:91] offset:1024 nt
	s_waitcnt vmcnt(15)
	global_store_dwordx4 v22, v[104:107], s[90:91] offset:2048 nt
	s_waitcnt vmcnt(15)
	global_store_dwordx4 v22, v[108:111], s[90:91] offset:3072 nt
	s_waitcnt vmcnt(15)
	global_store_dwordx4 v23, v[112:115], s[90:91] nt
	s_waitcnt vmcnt(15)
	global_store_dwordx4 v23, v[116:119], s[90:91] offset:1024 nt
	s_waitcnt vmcnt(15)
	global_store_dwordx4 v23, v[120:123], s[90:91] offset:2048 nt
	s_waitcnt vmcnt(15)
	global_store_dwordx4 v23, v[124:127], s[90:91] offset:3072 nt
	s_add_i32 s80, s101, s100
	s_branch .Lcpy1_loop
.Lcpy1_tail:
	s_cmp_lt_u32 s80, 0x3da0
	s_cbranch_scc0 .Lcpy1_end
	s_mul_hi_u32 s81, s80, 0x2ad5802b
	s_lshr_b32 s81, s81, 8
	s_mul_i32 s82, s81, 0x5fa
	s_sub_i32 s82, s80, s82
	s_lshl_b32 s82, s82, 13
	s_and_b32 s83, s81, 31
	s_mul_i32 s83, s83, 0xc00000
	s_add_i32 s82, s82, s83
	s_cmp_lt_u32 s81, 32
	s_cselect_b32 s84, s92, s94
	s_cselect_b32 s85, s93, s95
	s_mov_b32 s83, 0x1f210000
	s_cselect_b32 s83, 0x7210000, s83
	s_add_u32 s84, s84, s82
	s_addc_u32 s85, s85, 0
	s_add_u32 s84, s84, 0xc000
	s_addc_u32 s85, s85, 0
	s_add_u32 s83, s83, s82
	s_add_u32 s86, s98, s83
	s_addc_u32 s87, s99, 0
	global_load_dwordx4 v[64:67], v22, s[84:85] nt
	global_load_dwordx4 v[68:71], v22, s[84:85] offset:1024 nt
	global_load_dwordx4 v[72:75], v22, s[84:85] offset:2048 nt
	global_load_dwordx4 v[76:79], v22, s[84:85] offset:3072 nt
	global_load_dwordx4 v[80:83], v23, s[84:85] nt
	global_load_dwordx4 v[84:87], v23, s[84:85] offset:1024 nt
	global_load_dwordx4 v[88:91], v23, s[84:85] offset:2048 nt
	global_load_dwordx4 v[92:95], v23, s[84:85] offset:3072 nt
	s_waitcnt vmcnt(7)
	global_store_dwordx4 v22, v[64:67], s[86:87] nt
	s_waitcnt vmcnt(7)
	global_store_dwordx4 v22, v[68:71], s[86:87] offset:1024 nt
	s_waitcnt vmcnt(7)
	global_store_dwordx4 v22, v[72:75], s[86:87] offset:2048 nt
	s_waitcnt vmcnt(7)
	global_store_dwordx4 v22, v[76:79], s[86:87] offset:3072 nt
	s_waitcnt vmcnt(7)
	global_store_dwordx4 v23, v[80:83], s[86:87] nt
	s_waitcnt vmcnt(7)
	global_store_dwordx4 v23, v[84:87], s[86:87] offset:1024 nt
	s_waitcnt vmcnt(7)
	global_store_dwordx4 v23, v[88:91], s[86:87] offset:2048 nt
	s_waitcnt vmcnt(7)
	global_store_dwordx4 v23, v[92:95], s[86:87] offset:3072 nt

.LBB0_514:
	s_cmp_lt_u32 s33, 32
	s_cbranch_scc1 .Lcpy2_end
	v_lshrrev_b32_e32 v21, 6, v174
	v_and_b32_e32 v22, 63, v174
	v_lshlrev_b32_e32 v22, 4, v22
	v_readfirstlane_b32 s80, v21
	v_add_u32_e32 v23, 0x1000, v22
	v_readfirstlane_b32 s92, v235
	v_readfirstlane_b32 s93, v236
	v_readfirstlane_b32 s94, v237
	v_readfirstlane_b32 s95, v238
	v_readfirstlane_b32 s98, v239
	v_readfirstlane_b32 s99, v240
	s_add_i32 s80, s80, s33
	s_add_i32 s80, s80, 0x3d80
	s_sub_i32 s100, s78, 4
	s_lshl_b32 s100, s100, 3
.Lcpy2_loop:
	s_add_i32 s101, s80, s100
	s_cmp_lt_u32 s101, 0x7b40
	s_cbranch_scc0 .Lcpy2_tail
	s_mul_hi_u32 s81, s80, 0x2ad5802b
	s_lshr_b32 s81, s81, 8
	s_mul_i32 s82, s81, 0x5fa
	s_sub_i32 s82, s80, s82
	s_lshl_b32 s82, s82, 13
	s_and_b32 s83, s81, 31
	s_mul_i32 s83, s83, 0xc00000
	s_add_i32 s82, s82, s83
	s_cmp_lt_u32 s81, 32
	s_cselect_b32 s84, s92, s94
	s_cselect_b32 s85, s93, s95
	s_mov_b32 s83, 0x1f210000
	s_cselect_b32 s83, 0x7210000, s83
	s_add_u32 s84, s84, s82
	s_addc_u32 s85, s85, 0
	s_add_u32 s84, s84, 0xc000
	s_addc_u32 s85, s85, 0
	s_add_u32 s83, s83, s82
	s_add_u32 s86, s98, s83
	s_addc_u32 s87, s99, 0
	s_mul_hi_u32 s81, s101, 0x2ad5802b
	s_lshr_b32 s81, s81, 8
	s_mul_i32 s82, s81, 0x5fa
	s_sub_i32 s82, s101, s82
	s_lshl_b32 s82, s82, 13
	s_and_b32 s83, s81, 31
	s_mul_i32 s83, s83, 0xc00000
	s_add_i32 s82, s82, s83
	s_cmp_lt_u32 s81, 32
	s_cselect_b32 s88, s92, s94
	s_cselect_b32 s89, s93, s95
	s_mov_b32 s83, 0x1f210000
	s_cselect_b32 s83, 0x7210000, s83
	s_add_u32 s88, s88, s82
	s_addc_u32 s89, s89, 0
	s_add_u32 s88, s88, 0xc000
	s_addc_u32 s89, s89, 0
	s_add_u32 s83, s83, s82
	s_add_u32 s90, s98, s83
	s_addc_u32 s91, s99, 0
	global_load_dwordx4 v[64:67], v22, s[84:85] nt
	global_load_dwordx4 v[68:71], v22, s[84:85] offset:1024 nt
	global_load_dwordx4 v[72:75], v22, s[84:85] offset:2048 nt
	global_load_dwordx4 v[76:79], v22, s[84:85] offset:3072 nt
	global_load_dwordx4 v[80:83], v23, s[84:85] nt
	global_load_dwordx4 v[84:87], v23, s[84:85] offset:1024 nt
	global_load_dwordx4 v[88:91], v23, s[84:85] offset:2048 nt
	global_load_dwordx4 v[92:95], v23, s[84:85] offset:3072 nt
	global_load_dwordx4 v[96:99], v22, s[88:89] nt
	global_load_dwordx4 v[100:103], v22, s[88:89] offset:1024 nt
	global_load_dwordx4 v[104:107], v22, s[88:89] offset:2048 nt
	global_load_dwordx4 v[108:111], v22, s[88:89] offset:3072 nt
	global_load_dwordx4 v[112:115], v23, s[88:89] nt
	global_load_dwordx4 v[116:119], v23, s[88:89] offset:1024 nt
	global_load_dwordx4 v[120:123], v23, s[88:89] offset:2048 nt
	global_load_dwordx4 v[124:127], v23, s[88:89] offset:3072 nt
	s_waitcnt vmcnt(15)
	global_store_dwordx4 v22, v[64:67], s[86:87] nt
	s_waitcnt vmcnt(15)
	global_store_dwordx4 v22, v[68:71], s[86:87] offset:1024 nt
	s_waitcnt vmcnt(15)
	global_store_dwordx4 v22, v[72:75], s[86:87] offset:2048 nt
	s_waitcnt vmcnt(15)
	global_store_dwordx4 v22, v[76:79], s[86:87] offset:3072 nt
	s_waitcnt vmcnt(15)
	global_store_dwordx4 v23, v[80:83], s[86:87] nt
	s_waitcnt vmcnt(15)
	global_store_dwordx4 v23, v[84:87], s[86:87] offset:1024 nt
	s_waitcnt vmcnt(15)
	global_store_dwordx4 v23, v[88:91], s[86:87] offset:2048 nt
	s_waitcnt vmcnt(15)
	global_store_dwordx4 v23, v[92:95], s[86:87] offset:3072 nt
	s_waitcnt vmcnt(15)
	global_store_dwordx4 v22, v[96:99], s[90:91] nt
	s_waitcnt vmcnt(15)
	global_store_dwordx4 v22, v[100:103], s[90:91] offset:1024 nt
	s_waitcnt vmcnt(15)
	global_store_dwordx4 v22, v[104:107], s[90:91] offset:2048 nt
	s_waitcnt vmcnt(15)
	global_store_dwordx4 v22, v[108:111], s[90:91] offset:3072 nt
	s_waitcnt vmcnt(15)
	global_store_dwordx4 v23, v[112:115], s[90:91] nt
	s_waitcnt vmcnt(15)
	global_store_dwordx4 v23, v[116:119], s[90:91] offset:1024 nt
	s_waitcnt vmcnt(15)
	global_store_dwordx4 v23, v[120:123], s[90:91] offset:2048 nt
	s_waitcnt vmcnt(15)
	global_store_dwordx4 v23, v[124:127], s[90:91] offset:3072 nt
	s_add_i32 s80, s101, s100
	s_branch .Lcpy2_loop
.Lcpy2_tail:
	s_cmp_lt_u32 s80, 0x7b40
	s_cbranch_scc0 .Lcpy2_end
	s_mul_hi_u32 s81, s80, 0x2ad5802b
	s_lshr_b32 s81, s81, 8
	s_mul_i32 s82, s81, 0x5fa
	s_sub_i32 s82, s80, s82
	s_lshl_b32 s82, s82, 13
	s_and_b32 s83, s81, 31
	s_mul_i32 s83, s83, 0xc00000
	s_add_i32 s82, s82, s83
	s_cmp_lt_u32 s81, 32
	s_cselect_b32 s84, s92, s94
	s_cselect_b32 s85, s93, s95
	s_mov_b32 s83, 0x1f210000
	s_cselect_b32 s83, 0x7210000, s83
	s_add_u32 s84, s84, s82
	s_addc_u32 s85, s85, 0
	s_add_u32 s84, s84, 0xc000
	s_addc_u32 s85, s85, 0
	s_add_u32 s83, s83, s82
	s_add_u32 s86, s98, s83
	s_addc_u32 s87, s99, 0
	global_load_dwordx4 v[64:67], v22, s[84:85] nt
	global_load_dwordx4 v[68:71], v22, s[84:85] offset:1024 nt
	global_load_dwordx4 v[72:75], v22, s[84:85] offset:2048 nt
	global_load_dwordx4 v[76:79], v22, s[84:85] offset:3072 nt
	global_load_dwordx4 v[80:83], v23, s[84:85] nt
	global_load_dwordx4 v[84:87], v23, s[84:85] offset:1024 nt
	global_load_dwordx4 v[88:91], v23, s[84:85] offset:2048 nt
	global_load_dwordx4 v[92:95], v23, s[84:85] offset:3072 nt
	s_waitcnt vmcnt(7)
	global_store_dwordx4 v22, v[64:67], s[86:87] nt
	s_waitcnt vmcnt(7)
	global_store_dwordx4 v22, v[68:71], s[86:87] offset:1024 nt
	s_waitcnt vmcnt(7)
	global_store_dwordx4 v22, v[72:75], s[86:87] offset:2048 nt
	s_waitcnt vmcnt(7)
	global_store_dwordx4 v22, v[76:79], s[86:87] offset:3072 nt
	s_waitcnt vmcnt(7)
	global_store_dwordx4 v23, v[80:83], s[86:87] nt
	s_waitcnt vmcnt(7)
	global_store_dwordx4 v23, v[84:87], s[86:87] offset:1024 nt
	s_waitcnt vmcnt(7)
	global_store_dwordx4 v23, v[88:91], s[86:87] offset:2048 nt
	s_waitcnt vmcnt(7)
	global_store_dwordx4 v23, v[92:95], s[86:87] offset:3072 nt

.LBB0_1022:
	s_cmp_lt_u32 s33, 32
	s_cbranch_scc1 .Lcpy3_end
	v_lshrrev_b32_e32 v21, 6, v174
	v_and_b32_e32 v22, 63, v174
	v_lshlrev_b32_e32 v22, 4, v22
	v_readfirstlane_b32 s80, v21
	v_add_u32_e32 v23, 0x1000, v22
	v_readfirstlane_b32 s92, v235
	v_readfirstlane_b32 s93, v236
	v_readfirstlane_b32 s94, v237
	v_readfirstlane_b32 s95, v238
	v_readfirstlane_b32 s98, v239
	v_readfirstlane_b32 s99, v240
	s_add_i32 s80, s80, s33
	s_add_i32 s80, s80, 0x7b20
	s_sub_i32 s100, s78, 4
	s_lshl_b32 s100, s100, 3
.Lcpy3_loop:
	s_add_i32 s101, s80, s100
	s_cmp_lt_u32 s101, 0xb8e0
	s_cbranch_scc0 .Lcpy3_tail
	s_mul_hi_u32 s81, s80, 0x2ad5802b
	s_lshr_b32 s81, s81, 8
	s_mul_i32 s82, s81, 0x5fa
	s_sub_i32 s82, s80, s82
	s_lshl_b32 s82, s82, 13
	s_and_b32 s83, s81, 31
	s_mul_i32 s83, s83, 0xc00000
	s_add_i32 s82, s82, s83
	s_cmp_lt_u32 s81, 32
	s_cselect_b32 s84, s92, s94
	s_cselect_b32 s85, s93, s95
	s_mov_b32 s83, 0x1f210000
	s_cselect_b32 s83, 0x7210000, s83
	s_add_u32 s84, s84, s82
	s_addc_u32 s85, s85, 0
	s_add_u32 s84, s84, 0xc000
	s_addc_u32 s85, s85, 0
	s_add_u32 s83, s83, s82
	s_add_u32 s86, s98, s83
	s_addc_u32 s87, s99, 0
	s_mul_hi_u32 s81, s101, 0x2ad5802b
	s_lshr_b32 s81, s81, 8
	s_mul_i32 s82, s81, 0x5fa
	s_sub_i32 s82, s101, s82
	s_lshl_b32 s82, s82, 13
	s_and_b32 s83, s81, 31
	s_mul_i32 s83, s83, 0xc00000
	s_add_i32 s82, s82, s83
	s_cmp_lt_u32 s81, 32
	s_cselect_b32 s88, s92, s94
	s_cselect_b32 s89, s93, s95
	s_mov_b32 s83, 0x1f210000
	s_cselect_b32 s83, 0x7210000, s83
	s_add_u32 s88, s88, s82
	s_addc_u32 s89, s89, 0
	s_add_u32 s88, s88, 0xc000
	s_addc_u32 s89, s89, 0
	s_add_u32 s83, s83, s82
	s_add_u32 s90, s98, s83
	s_addc_u32 s91, s99, 0
	global_load_dwordx4 v[64:67], v22, s[84:85] nt
	global_load_dwordx4 v[68:71], v22, s[84:85] offset:1024 nt
	global_load_dwordx4 v[72:75], v22, s[84:85] offset:2048 nt
	global_load_dwordx4 v[76:79], v22, s[84:85] offset:3072 nt
	global_load_dwordx4 v[80:83], v23, s[84:85] nt
	global_load_dwordx4 v[84:87], v23, s[84:85] offset:1024 nt
	global_load_dwordx4 v[88:91], v23, s[84:85] offset:2048 nt
	global_load_dwordx4 v[92:95], v23, s[84:85] offset:3072 nt
	global_load_dwordx4 v[96:99], v22, s[88:89] nt
	global_load_dwordx4 v[100:103], v22, s[88:89] offset:1024 nt
	global_load_dwordx4 v[104:107], v22, s[88:89] offset:2048 nt
	global_load_dwordx4 v[108:111], v22, s[88:89] offset:3072 nt
	global_load_dwordx4 v[112:115], v23, s[88:89] nt
	global_load_dwordx4 v[116:119], v23, s[88:89] offset:1024 nt
	global_load_dwordx4 v[120:123], v23, s[88:89] offset:2048 nt
	global_load_dwordx4 v[124:127], v23, s[88:89] offset:3072 nt
	s_waitcnt vmcnt(15)
	global_store_dwordx4 v22, v[64:67], s[86:87] nt
	s_waitcnt vmcnt(15)
	global_store_dwordx4 v22, v[68:71], s[86:87] offset:1024 nt
	s_waitcnt vmcnt(15)
	global_store_dwordx4 v22, v[72:75], s[86:87] offset:2048 nt
	s_waitcnt vmcnt(15)
	global_store_dwordx4 v22, v[76:79], s[86:87] offset:3072 nt
	s_waitcnt vmcnt(15)
	global_store_dwordx4 v23, v[80:83], s[86:87] nt
	s_waitcnt vmcnt(15)
	global_store_dwordx4 v23, v[84:87], s[86:87] offset:1024 nt
	s_waitcnt vmcnt(15)
	global_store_dwordx4 v23, v[88:91], s[86:87] offset:2048 nt
	s_waitcnt vmcnt(15)
	global_store_dwordx4 v23, v[92:95], s[86:87] offset:3072 nt
	s_waitcnt vmcnt(15)
	global_store_dwordx4 v22, v[96:99], s[90:91] nt
	s_waitcnt vmcnt(15)
	global_store_dwordx4 v22, v[100:103], s[90:91] offset:1024 nt
	s_waitcnt vmcnt(15)
	global_store_dwordx4 v22, v[104:107], s[90:91] offset:2048 nt
	s_waitcnt vmcnt(15)
	global_store_dwordx4 v22, v[108:111], s[90:91] offset:3072 nt
	s_waitcnt vmcnt(15)
	global_store_dwordx4 v23, v[112:115], s[90:91] nt
	s_waitcnt vmcnt(15)
	global_store_dwordx4 v23, v[116:119], s[90:91] offset:1024 nt
	s_waitcnt vmcnt(15)
	global_store_dwordx4 v23, v[120:123], s[90:91] offset:2048 nt
	s_waitcnt vmcnt(15)
	global_store_dwordx4 v23, v[124:127], s[90:91] offset:3072 nt
	s_add_i32 s80, s101, s100
	s_branch .Lcpy3_loop
.Lcpy3_tail:
	s_cmp_lt_u32 s80, 0xb8e0
	s_cbranch_scc0 .Lcpy3_end
	s_mul_hi_u32 s81, s80, 0x2ad5802b
	s_lshr_b32 s81, s81, 8
	s_mul_i32 s82, s81, 0x5fa
	s_sub_i32 s82, s80, s82
	s_lshl_b32 s82, s82, 13
	s_and_b32 s83, s81, 31
	s_mul_i32 s83, s83, 0xc00000
	s_add_i32 s82, s82, s83
	s_cmp_lt_u32 s81, 32
	s_cselect_b32 s84, s92, s94
	s_cselect_b32 s85, s93, s95
	s_mov_b32 s83, 0x1f210000
	s_cselect_b32 s83, 0x7210000, s83
	s_add_u32 s84, s84, s82
	s_addc_u32 s85, s85, 0
	s_add_u32 s84, s84, 0xc000
	s_addc_u32 s85, s85, 0
	s_add_u32 s83, s83, s82
	s_add_u32 s86, s98, s83
	s_addc_u32 s87, s99, 0
	global_load_dwordx4 v[64:67], v22, s[84:85] nt
	global_load_dwordx4 v[68:71], v22, s[84:85] offset:1024 nt
	global_load_dwordx4 v[72:75], v22, s[84:85] offset:2048 nt
	global_load_dwordx4 v[76:79], v22, s[84:85] offset:3072 nt
	global_load_dwordx4 v[80:83], v23, s[84:85] nt
	global_load_dwordx4 v[84:87], v23, s[84:85] offset:1024 nt
	global_load_dwordx4 v[88:91], v23, s[84:85] offset:2048 nt
	global_load_dwordx4 v[92:95], v23, s[84:85] offset:3072 nt
	s_waitcnt vmcnt(7)
	global_store_dwordx4 v22, v[64:67], s[86:87] nt
	s_waitcnt vmcnt(7)
	global_store_dwordx4 v22, v[68:71], s[86:87] offset:1024 nt
	s_waitcnt vmcnt(7)
	global_store_dwordx4 v22, v[72:75], s[86:87] offset:2048 nt
	s_waitcnt vmcnt(7)
	global_store_dwordx4 v22, v[76:79], s[86:87] offset:3072 nt
	s_waitcnt vmcnt(7)
	global_store_dwordx4 v23, v[80:83], s[86:87] nt
	s_waitcnt vmcnt(7)
	global_store_dwordx4 v23, v[84:87], s[86:87] offset:1024 nt
	s_waitcnt vmcnt(7)
	global_store_dwordx4 v23, v[88:91], s[86:87] offset:2048 nt
	s_waitcnt vmcnt(7)
	global_store_dwordx4 v23, v[92:95], s[86:87] offset:3072 nt

.LBB0_1523:
	s_cmp_lt_u32 s33, 32
	s_cbranch_scc1 .Lcpy4_end
	v_lshrrev_b32_e32 v21, 6, v174
	v_and_b32_e32 v22, 63, v174
	v_lshlrev_b32_e32 v22, 4, v22
	v_readfirstlane_b32 s80, v21
	v_add_u32_e32 v23, 0x1000, v22
	v_readfirstlane_b32 s92, v235
	v_readfirstlane_b32 s93, v236
	v_readfirstlane_b32 s94, v237
	v_readfirstlane_b32 s95, v238
	v_readfirstlane_b32 s98, v239
	v_readfirstlane_b32 s99, v240
	s_add_i32 s80, s80, s33
	s_add_i32 s80, s80, 0xb8c0
	s_sub_i32 s100, s78, 4
	s_lshl_b32 s100, s100, 3
.Lcpy4_loop:
	s_add_i32 s101, s80, s100
	s_cmp_lt_u32 s101, 0xf680
	s_cbranch_scc0 .Lcpy4_tail
	s_mul_hi_u32 s81, s80, 0x2ad5802b
	s_lshr_b32 s81, s81, 8
	s_mul_i32 s82, s81, 0x5fa
	s_sub_i32 s82, s80, s82
	s_lshl_b32 s82, s82, 13
	s_and_b32 s83, s81, 31
	s_mul_i32 s83, s83, 0xc00000
	s_add_i32 s82, s82, s83
	s_cmp_lt_u32 s81, 32
	s_cselect_b32 s84, s92, s94
	s_cselect_b32 s85, s93, s95
	s_mov_b32 s83, 0x1f210000
	s_cselect_b32 s83, 0x7210000, s83
	s_add_u32 s84, s84, s82
	s_addc_u32 s85, s85, 0
	s_add_u32 s84, s84, 0xc000
	s_addc_u32 s85, s85, 0
	s_add_u32 s83, s83, s82
	s_add_u32 s86, s98, s83
	s_addc_u32 s87, s99, 0
	s_mul_hi_u32 s81, s101, 0x2ad5802b
	s_lshr_b32 s81, s81, 8
	s_mul_i32 s82, s81, 0x5fa
	s_sub_i32 s82, s101, s82
	s_lshl_b32 s82, s82, 13
	s_and_b32 s83, s81, 31
	s_mul_i32 s83, s83, 0xc00000
	s_add_i32 s82, s82, s83
	s_cmp_lt_u32 s81, 32
	s_cselect_b32 s88, s92, s94
	s_cselect_b32 s89, s93, s95
	s_mov_b32 s83, 0x1f210000
	s_cselect_b32 s83, 0x7210000, s83
	s_add_u32 s88, s88, s82
	s_addc_u32 s89, s89, 0
	s_add_u32 s88, s88, 0xc000
	s_addc_u32 s89, s89, 0
	s_add_u32 s83, s83, s82
	s_add_u32 s90, s98, s83
	s_addc_u32 s91, s99, 0
	global_load_dwordx4 v[64:67], v22, s[84:85] nt
	global_load_dwordx4 v[68:71], v22, s[84:85] offset:1024 nt
	global_load_dwordx4 v[72:75], v22, s[84:85] offset:2048 nt
	global_load_dwordx4 v[76:79], v22, s[84:85] offset:3072 nt
	global_load_dwordx4 v[80:83], v23, s[84:85] nt
	global_load_dwordx4 v[84:87], v23, s[84:85] offset:1024 nt
	global_load_dwordx4 v[88:91], v23, s[84:85] offset:2048 nt
	global_load_dwordx4 v[92:95], v23, s[84:85] offset:3072 nt
	global_load_dwordx4 v[96:99], v22, s[88:89] nt
	global_load_dwordx4 v[100:103], v22, s[88:89] offset:1024 nt
	global_load_dwordx4 v[104:107], v22, s[88:89] offset:2048 nt
	global_load_dwordx4 v[108:111], v22, s[88:89] offset:3072 nt
	global_load_dwordx4 v[112:115], v23, s[88:89] nt
	global_load_dwordx4 v[116:119], v23, s[88:89] offset:1024 nt
	global_load_dwordx4 v[120:123], v23, s[88:89] offset:2048 nt
	global_load_dwordx4 v[124:127], v23, s[88:89] offset:3072 nt
	s_waitcnt vmcnt(15)
	global_store_dwordx4 v22, v[64:67], s[86:87] nt
	s_waitcnt vmcnt(15)
	global_store_dwordx4 v22, v[68:71], s[86:87] offset:1024 nt
	s_waitcnt vmcnt(15)
	global_store_dwordx4 v22, v[72:75], s[86:87] offset:2048 nt
	s_waitcnt vmcnt(15)
	global_store_dwordx4 v22, v[76:79], s[86:87] offset:3072 nt
	s_waitcnt vmcnt(15)
	global_store_dwordx4 v23, v[80:83], s[86:87] nt
	s_waitcnt vmcnt(15)
	global_store_dwordx4 v23, v[84:87], s[86:87] offset:1024 nt
	s_waitcnt vmcnt(15)
	global_store_dwordx4 v23, v[88:91], s[86:87] offset:2048 nt
	s_waitcnt vmcnt(15)
	global_store_dwordx4 v23, v[92:95], s[86:87] offset:3072 nt
	s_waitcnt vmcnt(15)
	global_store_dwordx4 v22, v[96:99], s[90:91] nt
	s_waitcnt vmcnt(15)
	global_store_dwordx4 v22, v[100:103], s[90:91] offset:1024 nt
	s_waitcnt vmcnt(15)
	global_store_dwordx4 v22, v[104:107], s[90:91] offset:2048 nt
	s_waitcnt vmcnt(15)
	global_store_dwordx4 v22, v[108:111], s[90:91] offset:3072 nt
	s_waitcnt vmcnt(15)
	global_store_dwordx4 v23, v[112:115], s[90:91] nt
	s_waitcnt vmcnt(15)
	global_store_dwordx4 v23, v[116:119], s[90:91] offset:1024 nt
	s_waitcnt vmcnt(15)
	global_store_dwordx4 v23, v[120:123], s[90:91] offset:2048 nt
	s_waitcnt vmcnt(15)
	global_store_dwordx4 v23, v[124:127], s[90:91] offset:3072 nt
	s_add_i32 s80, s101, s100
	s_branch .Lcpy4_loop
.Lcpy4_tail:
	s_cmp_lt_u32 s80, 0xf680
	s_cbranch_scc0 .Lcpy4_end
	s_mul_hi_u32 s81, s80, 0x2ad5802b
	s_lshr_b32 s81, s81, 8
	s_mul_i32 s82, s81, 0x5fa
	s_sub_i32 s82, s80, s82
	s_lshl_b32 s82, s82, 13
	s_and_b32 s83, s81, 31
	s_mul_i32 s83, s83, 0xc00000
	s_add_i32 s82, s82, s83
	s_cmp_lt_u32 s81, 32
	s_cselect_b32 s84, s92, s94
	s_cselect_b32 s85, s93, s95
	s_mov_b32 s83, 0x1f210000
	s_cselect_b32 s83, 0x7210000, s83
	s_add_u32 s84, s84, s82
	s_addc_u32 s85, s85, 0
	s_add_u32 s84, s84, 0xc000
	s_addc_u32 s85, s85, 0
	s_add_u32 s83, s83, s82
	s_add_u32 s86, s98, s83
	s_addc_u32 s87, s99, 0
	global_load_dwordx4 v[64:67], v22, s[84:85] nt
	global_load_dwordx4 v[68:71], v22, s[84:85] offset:1024 nt
	global_load_dwordx4 v[72:75], v22, s[84:85] offset:2048 nt
	global_load_dwordx4 v[76:79], v22, s[84:85] offset:3072 nt
	global_load_dwordx4 v[80:83], v23, s[84:85] nt
	global_load_dwordx4 v[84:87], v23, s[84:85] offset:1024 nt
	global_load_dwordx4 v[88:91], v23, s[84:85] offset:2048 nt
	global_load_dwordx4 v[92:95], v23, s[84:85] offset:3072 nt
	s_waitcnt vmcnt(7)
	global_store_dwordx4 v22, v[64:67], s[86:87] nt
	s_waitcnt vmcnt(7)
	global_store_dwordx4 v22, v[68:71], s[86:87] offset:1024 nt
	s_waitcnt vmcnt(7)
	global_store_dwordx4 v22, v[72:75], s[86:87] offset:2048 nt
	s_waitcnt vmcnt(7)
	global_store_dwordx4 v22, v[76:79], s[86:87] offset:3072 nt
	s_waitcnt vmcnt(7)
	global_store_dwordx4 v23, v[80:83], s[86:87] nt
	s_waitcnt vmcnt(7)
	global_store_dwordx4 v23, v[84:87], s[86:87] offset:1024 nt
	s_waitcnt vmcnt(7)
	global_store_dwordx4 v23, v[88:91], s[86:87] offset:2048 nt
	s_waitcnt vmcnt(7)
	global_store_dwordx4 v23, v[92:95], s[86:87] offset:3072 nt

	.amdhsa_kernel _Z8yoco_fwd6Params
		.amdhsa_group_segment_fixed_size 0
		.amdhsa_private_segment_fixed_size 0
		.amdhsa_kernarg_size 480
		.amdhsa_user_sgpr_count 2
		.amdhsa_user_sgpr_dispatch_ptr 0
		.amdhsa_user_sgpr_queue_ptr 0
		.amdhsa_user_sgpr_kernarg_segment_ptr 1
		.amdhsa_user_sgpr_dispatch_id 0
		.amdhsa_user_sgpr_kernarg_preload_length 0
		.amdhsa_user_sgpr_kernarg_preload_offset 0
		.amdhsa_user_sgpr_private_segment_size 0
		.amdhsa_uses_dynamic_stack 0
		.amdhsa_enable_private_segment 0
		.amdhsa_system_sgpr_workgroup_id_x 1
		.amdhsa_system_sgpr_workgroup_id_y 0
		.amdhsa_system_sgpr_workgroup_id_z 0
		.amdhsa_system_sgpr_workgroup_info 0
		.amdhsa_system_vgpr_workitem_id 2
		.amdhsa_next_free_vgpr 256
		.amdhsa_next_free_sgpr 102
		.amdhsa_accum_offset 256
		.amdhsa_reserve_vcc 1
		.amdhsa_float_round_mode_32 0
		.amdhsa_float_round_mode_16_64 0
		.amdhsa_float_denorm_mode_32 3
		.amdhsa_float_denorm_mode_16_64 3
		.amdhsa_dx10_clamp 1
		.amdhsa_ieee_mode 1
		.amdhsa_fp16_overflow 0
		.amdhsa_tg_split 0
		.amdhsa_exception_fp_ieee_invalid_op 0
		.amdhsa_exception_fp_denorm_src 0
		.amdhsa_exception_fp_ieee_div_zero 0
		.amdhsa_exception_fp_ieee_overflow 0
		.amdhsa_exception_fp_ieee_underflow 0
		.amdhsa_exception_fp_ieee_inexact 0
		.amdhsa_exception_int_div_zero 0
	.end_amdhsa_kernel

amdhsa.kernels:
  - .agpr_count:     0
    .args:
      - .offset:         0
        .size:           224
        .value_kind:     by_value
      - .offset:         224
        .size:           4
        .value_kind:     hidden_block_count_x
      - .offset:         228
        .size:           4
        .value_kind:     hidden_block_count_y
      - .offset:         232
        .size:           4
        .value_kind:     hidden_block_count_z
      - .offset:         236
        .size:           2
        .value_kind:     hidden_group_size_x
      - .offset:         238
        .size:           2
        .value_kind:     hidden_group_size_y
      - .offset:         240
        .size:           2
        .value_kind:     hidden_group_size_z
      - .offset:         242
        .size:           2
        .value_kind:     hidden_remainder_x
      - .offset:         244
        .size:           2
        .value_kind:     hidden_remainder_y
      - .offset:         246
        .size:           2
        .value_kind:     hidden_remainder_z
      - .offset:         264
        .size:           8
        .value_kind:     hidden_global_offset_x
      - .offset:         272
        .size:           8
        .value_kind:     hidden_global_offset_y
      - .offset:         280
        .size:           8
        .value_kind:     hidden_global_offset_z
      - .offset:         288
        .size:           2
        .value_kind:     hidden_grid_dims
      - .offset:         312
        .size:           8
        .value_kind:     hidden_multigrid_sync_arg
      - .offset:         344
        .size:           4
        .value_kind:     hidden_dynamic_lds_size
    .group_segment_fixed_size: 0
    .kernarg_segment_align: 8
    .kernarg_segment_size: 480
    .language:       OpenCL C
    .language_version:
      - 2
      - 0
    .max_flat_workgroup_size: 512
    .name:           _Z8yoco_fwd6Params
    .private_segment_fixed_size: 0
    .sgpr_count:     108
    .sgpr_spill_count: 8
    .symbol:         _Z8yoco_fwd6Params.kd
    .uniform_work_group_size: 1
    .uses_dynamic_stack: false
    .vgpr_count:     256
    .vgpr_spill_count: 0
    .wavefront_size: 64
